# cmpsel: candidate selection for the top-k bisection rewritten (4-way select per element instead of hipcc's 16-way cndmask chains)
# speedup vs baseline: 1.0023x; 1.0023x over previous
.LBB0_717:
	s_or_b64 exec, exec, s[0:1]
	v_cmp_gt_u32_e64 s[0:1], 16, v251
	v_add_f32_e32 v80, v2, v80
	v_pk_add_f32 v[54:55], v[54:55], v[72:73]
	v_writelane_b32 v254, s0, 55
	v_pk_add_f32 v[60:61], v[56:57], v[60:61]
	v_pk_add_f32 v[56:57], v[52:53], v[64:65]
	v_pk_add_f32 v[62:63], v[58:59], v[62:63]
	v_pk_add_f32 v[58:59], v[66:67], v[74:75]
	v_pk_add_f32 v[64:65], v[68:69], v[70:71]
	v_add_f32_e32 v66, v81, v82
	v_pk_add_f32 v[52:53], v[76:77], v[78:79]
	v_writelane_b32 v254, s1, 56
	v_cmp_lt_u32_e64 s[2:3], 15, v251
	s_mov_b64 s[0:1], exec
	s_nop 0
	v_writelane_b32 v254, s2, 57
	s_nop 1
	v_writelane_b32 v254, s3, 58
	s_and_b64 s[2:3], s[0:1], s[2:3]
	s_xor_b64 s[0:1], s[2:3], s[0:1]
	v_writelane_b32 v254, s0, 59
	s_nop 1
	v_writelane_b32 v254, s1, 60
	s_mov_b64 exec, s[2:3]
	s_cbranch_execz .LBB0_723
	v_cmp_eq_u32_e64 s[20:21], 1, v253
	v_cmp_eq_u32_e64 s[16:17], 2, v253
	v_cmp_eq_u32_e64 s[18:19], 3, v253
	v_lshl_add_u32 v76, v253, 3, v206
	v_add_u32_e32 v2, -2, v251
	v_cndmask_b32_e64 v67, v80, v57, s[20:21]
	v_cndmask_b32_e64 v67, v67, v55, s[16:17]
	v_cndmask_b32_e64 v67, v67, v59, s[18:19]
	v_add_u32_e32 v181, -1, v76
	v_cmp_ge_u32_e64 s[0:1], v181, v2
	v_cndmask_b32_e64 v68, v62, v60, s[20:21]
	v_cndmask_b32_e64 v68, v68, v64, s[16:17]
	v_cndmask_b32_e64 v68, v68, v52, s[18:19]
	v_add_u32_e32 v182, 0, v76
	v_cmp_ge_u32_e32 vcc, v182, v2
	v_cndmask_b32_e64 v67, v67, 0, s[0:1]
	v_cndmask_b32_e64 v69, v63, v61, s[20:21]
	v_cndmask_b32_e64 v69, v69, v65, s[16:17]
	v_cndmask_b32_e64 v69, v69, v66, s[18:19]
	v_add_u32_e32 v183, 1, v76
	v_cmp_ge_u32_e64 s[0:1], v183, v2
	v_cndmask_b32_e64 v68, v68, 0, vcc
	v_cndmask_b32_e64 v70, v56, v54, s[20:21]
	v_cndmask_b32_e64 v70, v70, v58, s[16:17]
	v_cndmask_b32_e64 v70, v70, v53, s[18:19]
	v_add_u32_e32 v181, 2, v76
	v_cmp_ge_u32_e32 vcc, v181, v2
	v_cndmask_b32_e64 v69, v69, 0, s[0:1]
	v_cndmask_b32_e64 v71, v36, v40, s[20:21]
	v_cndmask_b32_e64 v71, v71, v44, s[16:17]
	v_cndmask_b32_e64 v71, v71, v48, s[18:19]
	v_add_u32_e32 v182, 31, v76
	v_cmp_ge_u32_e64 s[0:1], v182, v2
	v_cndmask_b32_e64 v70, v70, 0, vcc
	v_cndmask_b32_e64 v72, v37, v41, s[20:21]
	v_cndmask_b32_e64 v72, v72, v45, s[16:17]
	v_cndmask_b32_e64 v72, v72, v49, s[18:19]
	v_add_u32_e32 v183, 32, v76
	v_cmp_ge_u32_e32 vcc, v183, v2
	v_cndmask_b32_e64 v71, v71, 0, s[0:1]
	v_cndmask_b32_e64 v73, v38, v42, s[20:21]
	v_cndmask_b32_e64 v73, v73, v46, s[16:17]
	v_cndmask_b32_e64 v73, v73, v50, s[18:19]
	v_add_u32_e32 v181, 33, v76
	v_cmp_ge_u32_e64 s[0:1], v181, v2
	v_cndmask_b32_e64 v72, v72, 0, vcc
	v_cndmask_b32_e64 v74, v39, v43, s[20:21]
	v_cndmask_b32_e64 v74, v74, v47, s[16:17]
	v_cndmask_b32_e64 v74, v74, v51, s[18:19]
	v_add_u32_e32 v182, 34, v76
	v_cmp_ge_u32_e32 vcc, v182, v2
	v_cndmask_b32_e64 v73, v73, 0, s[0:1]
	v_cndmask_b32_e64 v75, v20, v24, s[20:21]
	v_cndmask_b32_e64 v75, v75, v28, s[16:17]
	v_cndmask_b32_e64 v75, v75, v32, s[18:19]
	v_add_u32_e32 v183, 63, v76
	v_cmp_ge_u32_e64 s[0:1], v183, v2
	v_cndmask_b32_e64 v74, v74, 0, vcc
	v_cndmask_b32_e64 v77, v21, v25, s[20:21]
	v_cndmask_b32_e64 v77, v77, v29, s[16:17]
	v_cndmask_b32_e64 v77, v77, v33, s[18:19]
	v_add_u32_e32 v181, 64, v76
	v_cmp_ge_u32_e32 vcc, v181, v2
	v_cndmask_b32_e64 v75, v75, 0, s[0:1]
	v_cndmask_b32_e64 v78, v22, v26, s[20:21]
	v_cndmask_b32_e64 v78, v78, v30, s[16:17]
	v_cndmask_b32_e64 v78, v78, v34, s[18:19]
	v_add_u32_e32 v182, 0x41, v76
	v_cmp_ge_u32_e64 s[0:1], v182, v2
	v_cndmask_b32_e64 v77, v77, 0, vcc
	v_cndmask_b32_e64 v79, v23, v27, s[20:21]
	v_cndmask_b32_e64 v79, v79, v31, s[16:17]
	v_cndmask_b32_e64 v79, v79, v35, s[18:19]
	v_add_u32_e32 v183, 0x42, v76
	v_cmp_ge_u32_e32 vcc, v183, v2
	v_cndmask_b32_e64 v78, v78, 0, s[0:1]
	v_cndmask_b32_e64 v81, v4, v8, s[20:21]
	v_cndmask_b32_e64 v81, v81, v12, s[16:17]
	v_cndmask_b32_e64 v81, v81, v16, s[18:19]
	v_add_u32_e32 v181, 0x5f, v76
	v_cmp_ge_u32_e64 s[0:1], v181, v2
	v_cndmask_b32_e64 v79, v79, 0, vcc
	v_cndmask_b32_e64 v82, v5, v9, s[20:21]
	v_cndmask_b32_e64 v82, v82, v13, s[16:17]
	v_cndmask_b32_e64 v82, v82, v17, s[18:19]
	v_add_u32_e32 v182, 0x60, v76
	v_cmp_ge_u32_e32 vcc, v182, v2
	v_cndmask_b32_e64 v81, v81, 0, s[0:1]
	v_cndmask_b32_e64 v83, v6, v10, s[20:21]
	v_cndmask_b32_e64 v83, v83, v14, s[16:17]
	v_cndmask_b32_e64 v83, v83, v18, s[18:19]
	v_add_u32_e32 v183, 0x61, v76
	v_cmp_ge_u32_e64 s[0:1], v183, v2
	v_cndmask_b32_e64 v82, v82, 0, vcc
	v_cndmask_b32_e64 v180, v7, v11, s[20:21]
	v_cndmask_b32_e64 v180, v180, v15, s[16:17]
	v_cndmask_b32_e64 v180, v180, v19, s[18:19]
	v_add_u32_e32 v181, 0x62, v76
	v_cmp_ge_u32_e32 vcc, v181, v2
	v_cndmask_b32_e64 v83, v83, 0, s[0:1]
	s_nop 1
	v_cndmask_b32_e64 v180, v180, 0, vcc
	v_max_u32_e32 v76, v68, v67
	v_max3_u32 v76, v70, v69, v76
	v_max3_u32 v76, v72, v71, v76
	v_max3_u32 v76, v74, v73, v76
	v_max3_u32 v76, v77, v75, v76
	v_max3_u32 v76, v79, v78, v76
	v_max3_u32 v76, v82, v81, v76
	v_max3_u32 v76, v180, v83, v76
	s_nop 1
	v_max_i32_dpp v76, v76, v76 quad_perm:[1,0,3,2] row_mask:0xf bank_mask:0xf bound_ctrl:1
	s_nop 1
	v_max_i32_dpp v76, v76, v76 quad_perm:[2,3,0,1] row_mask:0xf bank_mask:0xf bound_ctrl:1
	ds_bpermute_b32 v181, v252, v76
	s_waitcnt lgkmcnt(0)
	v_max_i32_e32 v76, v76, v181
	v_or_b32_e32 v181, 1, v76
	v_ffbh_u32_e32 v181, v181
	v_xor_b32_e32 v181, 31, v181
	v_cvt_f32_u32_e32 v181, v181
	v_cmp_lt_f32_e32 vcc, 0, v76
	s_nop 1
	v_cndmask_b32_e32 v76, 0, v181, vcc
	v_xor_b32_e32 v181, 1, v229
	v_cmp_lt_i32_e32 vcc, v181, v245
	s_nop 1
	v_cndmask_b32_e32 v181, v229, v181, vcc
	v_lshlrev_b32_e32 v181, 2, v181
	ds_bpermute_b32 v181, v181, v76
	s_waitcnt lgkmcnt(0)
	v_max_f32_e32 v181, v181, v181
	v_max_f32_e32 v76, v76, v181
	v_xor_b32_e32 v181, 2, v229
	v_cmp_lt_i32_e32 vcc, v181, v245
	s_nop 1
	v_cndmask_b32_e32 v181, v229, v181, vcc
	v_lshlrev_b32_e32 v181, 2, v181
	ds_bpermute_b32 v181, v181, v76
	s_waitcnt lgkmcnt(0)
	v_max_f32_e32 v181, v181, v181
	v_max_f32_e32 v76, v76, v181
	v_xor_b32_e32 v181, 4, v229
	v_cmp_lt_i32_e32 vcc, v181, v245
	s_nop 1
	v_cndmask_b32_e32 v181, v229, v181, vcc
	v_lshlrev_b32_e32 v181, 2, v181
	ds_bpermute_b32 v181, v181, v76
	s_waitcnt lgkmcnt(0)
	v_max_f32_e32 v181, v181, v181
	v_max_f32_e32 v76, v76, v181
	v_xor_b32_e32 v181, 8, v229
	v_cmp_lt_i32_e32 vcc, v181, v245
	s_nop 1
	v_cndmask_b32_e32 v181, v229, v181, vcc
	v_lshlrev_b32_e32 v181, 2, v181
	ds_bpermute_b32 v181, v181, v76
	s_waitcnt lgkmcnt(0)
	v_max_f32_e32 v181, v181, v181
	v_max_f32_e32 v76, v76, v181
	v_xor_b32_e32 v181, 16, v229
	v_cmp_lt_i32_e32 vcc, v181, v245
	s_nop 1
	v_cndmask_b32_e32 v181, v229, v181, vcc
	v_lshlrev_b32_e32 v181, 2, v181
	ds_bpermute_b32 v181, v181, v76
	s_waitcnt lgkmcnt(0)
	v_max_f32_e32 v181, v181, v181
	v_max_f32_e32 v76, v76, v181
	ds_bpermute_b32 v181, v252, v76
	s_waitcnt lgkmcnt(0)
	v_max_f32_e32 v181, v181, v181
	v_max_f32_e32 v76, v76, v181
	v_cvt_u32_f32_e32 v181, v76
	v_mov_b32_e32 v76, 0
	v_cmp_lt_i32_e32 vcc, -1, v181
	s_and_saveexec_b64 s[2:3], vcc
	s_cbranch_execz .LBB0_722
	v_mov_b32_e32 v76, 0
	s_mov_b64 s[6:7], 0
	s_mov_b64 s[4:5], 0
